# P4 prologue: the row-stat loads are no longer waited before the first LDS-DMA tile loads, the wait moved to their first use as vmcnt(8)
# speedup vs baseline: 1.0015x; 1.0015x over previous
; #define PG8_STAGEX(b, gbase) do { if constexpr (XR) { if (lane < 16) __builtin_amdgcn_global_load_lds((const unsigned*)((const char*)(gbase) + voffX), (PG8_LAS unsigned*)(lds + XR_OFF + (b) * 2048 + wid * 256), 16, 0, 0); } } while (0)
; #define PG8_STAGE(bufoff, gbase, voff) do { _Pragma("unroll") for (int _i = 0; _i < 2; ++_i) \
;         __builtin_amdgcn_global_load_lds((const unsigned*)((const char*)(gbase) + (voff)[_i]), (PG8_LAS unsigned*)(lds + (bufoff) + ldsw + _i * 8192), 16, 0, 0); } while (0)
; template <class Epi, class Sched, bool ALIGN_EPI = false, bool SP2 = false, bool DRAIN = true, bool XR = false>
; __device__ __forceinline__ void gemm_phase(PG8_LAS unsigned char* lds, const Gemm g, const Sched& S, const Epi& E) {
;     int tid_ = threadIdx.x; asm volatile("" : "+v"(tid_));
;     const int tid = tid_, wid = __builtin_amdgcn_readfirstlane(tid >> 6), lane = tid & 63, wr = wid >> 2, wc = wid & 3, fr = lane & 15, fq = lane >> 4;
;     const int K = g.K, nt = K / BK, lda = g.lda ? g.lda : K;
;     unsigned voffA[2], voffB[2];
; #pragma unroll
;     for (int i = 0; i < 2; ++i) { int R, C; stage_rc(tid * 16 + i * 8192, R, C); const int Rb = Epi::PERM ? ((R & ~31) + perm32(R & 31)) : R;
;         voffA[i] = (unsigned)(R * lda + C) * 2u; voffB[i] = (unsigned)(Rb * K + C) * 2u; }
;     const size_t kstep = (size_t)(BK * 2);
;     const size_t hstep = (size_t)HALF * K * 2;
;     const size_t hstepA = (size_t)HALF * lda * 2;
;     const int t0 = g.t0, ntm = nt - 1;
;     const size_t kblkA = g.kblk ? (size_t)g.kblk : 4 * kstep;
;     const size_t tstep = 2 * hstep;
;     const unsigned ldsw = (unsigned)wid * 1024u;
;     const int aoff = lds_byte(wr * 64 + fr, fq * 8), boff = lds_byte(wc * 32 + fr, fq * 8);
;     static_assert(!XR || SP2, "extra rows: SP2 body only");
;     unsigned voffX = 0; const int aoffx = lds_byte(fr, fq * 8);
;     if constexpr (XR) { int R, C; stage_rc(wid * 256 + (lane & 15) * 16, R, C); voffX = (unsigned)(R * g.ldax + C) * 2u; }
;     const size_t xstep = (size_t)16 * (XR ? g.ldax : 0) * 2;
;     ...
;     if constexpr (SP2) {
;         PG8_STAGE(PG8_SB(0, 0), cB + kb0, voffB); PG8_STAGE(PG8_SB(0, 1), cB + kb0 + hstep, voffB); PG8_STAGE(PG8_SA(0, 0), cA + ka0, voffA); PG8_STAGEX(0, cX + kx0); PG8_STAGE(PG8_SA(0, 1), cA + ka0 + hstepA, voffA);
.LBB0_1166:
	s_and_b64 vcc, exec, s[0:1]
	s_cbranch_vccnz .LBB0_1265
	v_bfe_i32 v5, v22, 27, 1
	v_lshlrev_b32_e32 v2, 4, v22
	v_lshrrev_b32_e32 v5, 22, v5
	v_add_u32_e32 v5, v2, v5
	v_and_b32_e32 v5, 0xfffffc00, v5
	v_sub_u32_e32 v5, v2, v5
	v_lshrrev_b32_e32 v14, 4, v5
	v_ashrrev_i32_e32 v4, 31, v22
	v_bitop3_b32 v5, v14, v5, 32 bitop3:0x6c
	v_lshrrev_b32_e32 v4, 26, v4
	v_ashrrev_i32_e32 v15, 31, v5
	v_add_u32_e32 v4, v22, v4
	v_lshrrev_b32_e32 v15, 26, v15
	v_ashrrev_i32_e32 v4, 6, v4
	v_add_u32_e32 v15, v5, v15
	v_lshlrev_b32_e32 v14, 3, v4
	v_ashrrev_i32_e32 v16, 6, v15
	v_and_b32_e32 v15, 0xc0, v15
	v_and_b32_e32 v14, -16, v14
	v_lshlrev_b32_e32 v4, 5, v4
	v_sub_u32_e32 v5, v5, v15
	v_mov_b32_e32 v17, 1
	v_add_u32_e32 v14, v16, v14
	v_and_b32_e32 v4, 32, v4
	v_ashrrev_i16_sdwa v5, v17, sext(v5) dst_sel:DWORD dst_unused:UNUSED_PAD src0_sel:DWORD src1_sel:BYTE_0
	v_add_u32_sdwa v4, v4, sext(v5) dst_sel:DWORD dst_unused:UNUSED_PAD src0_sel:DWORD src1_sel:WORD_0
	v_lshlrev_b32_e32 v5, 1, v14
	v_lshrrev_b32_e32 v15, 2, v14
	v_and_b32_e32 v16, 3, v16
	s_mov_b32 s0, 0x7fffffe0
	v_and_b32_e32 v5, 24, v5
	v_and_b32_e32 v15, 4, v15
	v_and_or_b32 v16, v14, s0, v16
	v_or3_b32 v5, v16, v15, v5
	v_mul_lo_u32 v14, v14, s6
	v_mul_lo_u32 v5, v5, s6
	v_add_u32_e32 v2, 0x2000, v2
	v_add_lshl_u32 v214, v4, v14, 1
	v_add_lshl_u32 v216, v5, v4, 1
	v_ashrrev_i32_e32 v4, 31, v2
	v_lshrrev_b32_e32 v4, 22, v4
	v_add_u32_e32 v4, v2, v4
	v_ashrrev_i32_e32 v4, 10, v4
	v_mul_i32_i24_e32 v5, 0x400, v4
	v_sub_u32_e32 v2, v2, v5
	v_lshrrev_b32_e32 v5, 4, v2
	v_bitop3_b32 v2, v5, v2, 32 bitop3:0x6c
	v_ashrrev_i32_e32 v14, 31, v2
	v_lshrrev_b32_e32 v14, 26, v14
	s_ashr_i32 s34, s36, 6
	v_lshlrev_b32_e32 v5, 3, v4
	v_add_u32_e32 v14, v2, v14
	s_ashr_i32 s7, s6, 31
	v_and_b32_e32 v5, -16, v5
	v_ashrrev_i32_e32 v15, 6, v14
	s_lshl_b64 s[10:11], s[6:7], 8
	s_lshl_b64 s[12:13], s[6:7], 9
	s_lshl_b32 s16, s34, 10
	s_lshl_b32 s57, s34, 8
	v_add_u32_e32 v5, v15, v5
	v_and_b32_e32 v15, 3, v15
	s_add_u32 s19, s4, 0xbc00000
	v_and_or_b32 v15, v5, s0, v15
	s_addc_u32 s26, s5, 0
	v_readlane_b32 s0, v253, 28
	s_add_u32 s0, s4, s0
	s_addc_u32 s1, s5, 0
	s_add_u32 s17, s0, 0x480000
	s_addc_u32 s61, s1, 0
	s_add_u32 s62, s4, 0xdc00000
	s_addc_u32 s63, s5, 0
	s_ashr_i32 s2, s55, 31
	s_mul_i32 s2, s12, s2
	s_mul_hi_u32 s3, s12, s55
	s_add_i32 s14, s3, s2
	s_lshr_b64 s[2:3], s[6:7], 23
	s_mul_i32 s3, s2, s55
	s_add_i32 s3, s14, s3
	s_ashr_i32 s14, s56, 31
	s_ashr_i32 s0, s55, 1
	s_mul_i32 s14, s12, s14
	s_mul_hi_u32 s15, s12, s56
	s_ashr_i32 s1, s0, 31
	s_add_i32 s14, s15, s14
	s_mul_i32 s2, s2, s56
	v_and_b32_e32 v14, 0xc0, v14
	s_lshl_b64 s[0:1], s[0:1], 15
	s_add_i32 s2, s14, s2
	s_mul_i32 s14, s12, s56
	v_lshlrev_b32_e32 v4, 5, v4
	v_sub_u32_e32 v2, v2, v14
	s_add_u32 s14, s17, s14
	v_and_b32_e32 v4, 32, v4
	v_ashrrev_i16_sdwa v2, v17, sext(v2) dst_sel:DWORD dst_unused:UNUSED_PAD src0_sel:DWORD src1_sel:BYTE_0
	s_addc_u32 s15, s61, s2
	s_add_i32 s64, s16, 0
	v_add_u32_sdwa v2, v4, sext(v2) dst_sel:DWORD dst_unused:UNUSED_PAD src0_sel:DWORD src1_sel:WORD_0
	v_lshlrev_b32_e32 v4, 1, v5
	v_lshrrev_b32_e32 v14, 2, v5
	s_add_i32 s65, s64, 0x10000
	s_add_i32 s67, s64, 0x12000
	v_and_b32_e32 v4, 24, v4
	v_and_b32_e32 v14, 4, v14
	s_add_u32 s16, s62, s0
	v_or3_b32 v4, v15, v14, v4
	v_writelane_b32 v254, s17, 23
	s_addc_u32 s17, s63, s1
	v_mul_lo_u32 v4, v4, s6
	s_mov_b32 m0, s65
	s_add_u32 s24, s14, s10
	v_add_lshl_u32 v220, v4, v2, 1
	global_load_lds_dwordx4 v216, s[14:15]
	s_mov_b32 m0, s67
	s_addc_u32 s25, s15, s11
	s_add_i32 s68, s64, 0x14000
	s_mul_i32 s18, s12, s55
	global_load_lds_dwordx4 v220, s[14:15]
	s_mov_b32 m0, s68
	s_add_i32 s69, s64, 0x16000
	global_load_lds_dwordx4 v216, s[24:25]
	s_mov_b32 m0, s69
	s_add_u32 s18, s19, s18
	v_mul_lo_u32 v5, v5, s6
	global_load_lds_dwordx4 v220, s[24:25]
	v_writelane_b32 v253, s19, 41
	s_addc_u32 s19, s26, s3
	s_mov_b32 m0, s64
	s_add_i32 s70, s64, 0x2000
	v_add_lshl_u32 v218, v2, v5, 1
	global_load_lds_dwordx4 v214, s[18:19]
	s_mov_b32 m0, s70
	v_and_b32_e32 v237, 15, v22
	global_load_lds_dwordx4 v218, s[18:19]
	v_lshl_or_b32 v2, v237, 4, s57
	v_ashrrev_i32_e32 v4, 31, v2
	v_lshrrev_b32_e32 v4, 22, v4
	v_add_u32_e32 v4, v2, v4
	v_ashrrev_i32_e32 v4, 10, v4
	v_mul_i32_i24_e32 v5, 0x400, v4
	v_sub_u32_e32 v2, v2, v5
	v_lshrrev_b32_e32 v5, 4, v2
	v_bitop3_b32 v2, v5, v2, 32 bitop3:0x6c
	v_ashrrev_i32_e32 v14, 31, v2
	v_lshrrev_b32_e32 v14, 26, v14
	v_add_u32_e32 v14, v2, v14
	v_lshrrev_b32_e32 v15, 6, v14
	v_and_b32_e32 v14, 0xc0, v14
	v_lshlrev_b32_e32 v5, 3, v4
	v_lshlrev_b32_e32 v4, 5, v4
	v_sub_u32_e32 v2, v2, v14
	v_and_b32_e32 v5, 0x1ffff0, v5
	v_and_b32_e32 v4, 32, v4
	v_ashrrev_i16_sdwa v2, v17, sext(v2) dst_sel:DWORD dst_unused:UNUSED_PAD src0_sel:DWORD src1_sel:BYTE_0
	v_and_b32_e32 v25, 63, v22
	v_add_u32_sdwa v2, v4, sext(v2) dst_sel:DWORD dst_unused:UNUSED_PAD src0_sel:DWORD src1_sel:WORD_0
	v_add_lshl_u32 v4, v15, v5, 11
	v_writelane_b32 v253, s26, 33
	v_lshl_add_u32 v2, v2, 1, v4
	v_cmp_lt_u32_e64 s[0:1], 15, v25
	v_cmp_gt_u32_e64 s[2:3], 16, v25
	s_and_saveexec_b64 s[26:27], s[2:3]
	s_cbranch_execz .LBB0_1169
	s_add_i32 s28, s57, 0
	s_add_i32 m0, s28, 0x22400
	s_nop 0
	global_load_lds_dwordx4 v2, s[16:17]

;     __device__ __forceinline__ bool next(int i, Unit& u) const { if (i >= nr) return false; int j = nr - 1 - i + rot; if (j >= nr) j -= nr; const bool ok = StaticOrder::next(j, u); u.ui = i; return ok; }
;     __device__ __forceinline__ bool next(int i, Unit& u) const { if (c >= nM || i >= 2) return false; u.pm = c; u.pn = i; u.ui = i; return true; }
;     __host__ __device__ __forceinline__ bool next(int i, Unit& u) const {
;         const long L = (long)i * G + c; if (L >= nwg) return false;
;         int wgid = (int)L; { const int q = nwg / NXCD, r = nwg % NXCD, xcd = wgid % NXCD, off = wgid / NXCD; wgid = (xcd < r ? xcd * (q + 1) : r * (q + 1) + (xcd - r) * q) + off; }
;         const int nig = WGM * nN, gid = wgid / nig, fm = gid * WGM, gsz = (nM - fm) < WGM ? (nM - fm) : WGM;
;         u.pm = fm + ((wgid % nig) % gsz); u.pn = (wgid % nig) / gsz; u.ui = i; return true;
;     template <class Sched> __device__ __forceinline__ void prehook(const Sched& S, const Unit& u0) const {
;     ...
;                 for (int i_ = 0; i_ < 4 && S.next(i_, u_); ++i_) { f32x4 a = pre.a, b = pre.b; float q0 = pre.c[0], q1 = pre.c[1];
;                     if (u_.pm != u0.pm) { const size_t row = (size_t)u_.pm * 256 + t_; a = *(const f32x4*)(gs + row * 8); b = *(const f32x4*)(gs + row * 8 + 4); q0 = gq[row]; q1 = gq[gq_stride + row]; }
.LBB0_1174:
	s_ashr_i32 s28, s30, 3
	s_add_i32 s28, s31, s28
	s_ashr_i32 s29, s28, 31
	s_lshr_b32 s29, s29, 27
	s_add_i32 s29, s28, s29
	s_ashr_i32 s30, s29, 5
	s_and_b32 s29, s29, 0xffe0
	s_sub_i32 s28, s28, s29
	s_bfe_i32 s29, s28, 0x80000
	s_bfe_u32 s29, s29, 0x3000c
	s_add_i32 s29, s28, s29
	s_and_b32 s29, s29, 0xf8
	s_sub_i32 s28, s28, s29
	s_lshl_b32 s30, s30, 3
	s_sext_i32_i8 s28, s28
	s_add_i32 s28, s30, s28
	s_waitcnt vmcnt(8)
	v_mov_b64_e32 v[16:17], v[8:9]
	v_mov_b64_e32 v[20:21], v[12:13]
	v_ashrrev_i32_e32 v5, 31, v4
	s_cmp_eq_u32 s28, s55
	v_mov_b64_e32 v[14:15], v[6:7]
	v_mov_b32_e32 v26, v23
	v_mov_b32_e32 v27, v24
	v_mov_b64_e32 v[18:19], v[10:11]
	s_cbranch_scc1 .LBB0_1176
	s_ashr_i32 s29, s28, 31
	s_lshl_b64 s[28:29], s[28:29], 8
	v_lshl_add_u64 v[14:15], s[28:29], 0, v[4:5]
	v_lshlrev_b64 v[16:17], 5, v[14:15]
	v_lshl_add_u64 v[14:15], v[14:15], 2, s[22:23]
	v_lshl_add_u64 v[18:19], s[20:21], 0, v[16:17]
	v_add_co_u32_e32 v16, vcc, 0x10000, v14
	s_nop 1
	v_addc_co_u32_e32 v17, vcc, 0, v15, vcc
	global_load_dword v26, v[14:15], off
	global_load_dword v27, v[16:17], off
	s_nop 0
	global_load_dwordx4 v[14:17], v[18:19], off offset:16
	s_nop 0
	global_load_dwordx4 v[18:21], v[18:19], off
